# G4 (attention out-proj) also retiled to 192x256 tiles on all 256 CUs; per-32-row residual source and gate select
# speedup vs baseline: 1.0183x; 1.0081x over previous
.LBB0_264:
	s_andn2_b64 vcc, exec, s[0:1]
	s_cbranch_vccnz .LBB0_793
	s_mov_b64 s[0:1], src_shared_base
	s_add_i32 s0, 0, 0x2100c
	s_cmp_lg_u32 s0, -1
	s_cselect_b32 s0, s0, 0
	s_cselect_b32 s4, s1, 0
	v_mov_b32_e32 v2, s0
	s_add_i32 s0, 0, 0x21008
	s_cmp_lg_u32 s0, -1
	v_mov_b32_e32 v0, v224
	v_mov_b32_e32 v3, s4
	s_cselect_b32 s0, s0, 0
	s_cselect_b32 s1, s1, 0
	flat_load_dword v1, v[2:3] sc0 sc1
	s_waitcnt vmcnt(0)
	v_mov_b32_e32 v2, s0
	v_mov_b32_e32 v3, s1
	flat_load_dword v237, v[2:3] sc0 sc1
	s_waitcnt vmcnt(0) lgkmcnt(0)
	v_cmp_gt_i32_e32 vcc, 32, v237
	s_and_saveexec_b64 s[40:41], vcc
	v_readlane_b32 s18, v254, 24
	v_readlane_b32 s19, v254, 25
	s_cbranch_execz .LBB0_792
	v_lshlrev_b32_e32 v233, 3, v1
	v_ashrrev_i32_e32 v1, 31, v237
	v_lshrrev_b32_e32 v1, 30, v1
	v_add_u32_e32 v1, v237, v1
	v_lshrrev_b32_e32 v2, 2, v1
	v_and_b32_e32 v1, 0xfffffc, v1
	v_sub_u32_e32 v1, v237, v1
	v_lshlrev_b32_e32 v238, 8, v1
	v_lshrrev_b32_e32 v1, 4, v0
	v_xor_b32_e32 v1, v1, v0
	s_add_u32 s44, s66, 0x2d53700
	v_lshlrev_b32_e32 v1, 4, v1
	s_addc_u32 s45, s67, 0
	v_readlane_b32 s0, v254, 61
	v_add_u32_e32 v236, v2, v233
	v_mul_u32_u24_e32 v236, 0xc0, v236
	v_and_b32_e32 v128, 0x70, v1
	v_ashrrev_i32_e32 v1, 3, v0
	s_add_u32 s0, s66, s0
	v_add_u32_e32 v4, v236, v1
	s_addc_u32 s1, s67, 0
	v_ashrrev_i32_e32 v5, 31, v4
	v_lshl_add_u32 v6, v0, 4, 0
	s_add_u32 s46, s0, 0x84b700
	v_lshl_add_u64 v[2:3], s[44:45], 0, v[128:129]
	v_lshlrev_b64 v[4:5], 11, v[4:5]
	v_readfirstlane_b32 s0, v6
	v_add_u32_e32 v7, 0x200, v0
	v_lshl_add_u64 v[4:5], v[2:3], 0, v[4:5]
	s_mov_b32 m0, s0
	v_ashrrev_i32_e32 v8, 3, v7
	global_load_lds_dwordx4 v[4:5], off
	v_add_u32_e32 v4, v236, v8
	v_ashrrev_i32_e32 v5, 31, v4
	v_lshl_add_u32 v7, v7, 4, 0
	v_lshlrev_b64 v[4:5], 11, v[4:5]
	v_readfirstlane_b32 s0, v7
	v_add_u32_e32 v9, 0x400, v0
	v_lshl_add_u64 v[4:5], v[2:3], 0, v[4:5]
	s_mov_b32 m0, s0
	v_ashrrev_i32_e32 v10, 3, v9
	global_load_lds_dwordx4 v[4:5], off
	v_add_u32_e32 v4, v236, v10
	v_ashrrev_i32_e32 v5, 31, v4
	v_lshl_add_u32 v9, v9, 4, 0
	v_lshlrev_b64 v[4:5], 11, v[4:5]
	v_readfirstlane_b32 s0, v9
	v_add_u32_e32 v11, 0x600, v0
	v_lshl_add_u64 v[4:5], v[2:3], 0, v[4:5]
	s_mov_b32 m0, s0
	v_ashrrev_i32_e32 v12, 3, v11
	global_load_lds_dwordx4 v[4:5], off
	v_add_u32_e32 v4, v236, v12
	v_ashrrev_i32_e32 v5, 31, v4
	v_lshlrev_b64 v[4:5], 11, v[4:5]
	v_lshl_add_u32 v11, v11, 4, 0
	v_lshl_add_u64 v[2:3], v[2:3], 0, v[4:5]
	v_readfirstlane_b32 s0, v11
	v_add_u32_e32 v4, v238, v1
	s_addc_u32 s47, s1, 0
	s_mov_b32 m0, s0
	v_ashrrev_i32_e32 v5, 31, v4
	v_add_u32_e32 v1, 0x8000, v6
	v_lshl_add_u64 v[2:3], s[46:47], 0, v[128:129]
	v_lshlrev_b64 v[4:5], 11, v[4:5]
	v_readfirstlane_b32 s0, v1
	v_lshl_add_u64 v[4:5], v[2:3], 0, v[4:5]
	s_mov_b32 m0, s0
	v_add_u32_e32 v1, 0x8000, v7
	global_load_lds_dwordx4 v[4:5], off
	v_add_u32_e32 v4, v238, v8
	v_ashrrev_i32_e32 v5, 31, v4
	v_lshlrev_b64 v[4:5], 11, v[4:5]
	v_readfirstlane_b32 s0, v1
	v_lshl_add_u64 v[4:5], v[2:3], 0, v[4:5]
	s_mov_b32 m0, s0
	v_add_u32_e32 v1, 0x8000, v9
	global_load_lds_dwordx4 v[4:5], off
	v_add_u32_e32 v4, v238, v10
	v_ashrrev_i32_e32 v5, 31, v4
	v_lshlrev_b64 v[4:5], 11, v[4:5]
	v_readfirstlane_b32 s0, v1
	v_lshl_add_u64 v[4:5], v[2:3], 0, v[4:5]
	s_mov_b32 m0, s0
	v_add_u32_e32 v1, 0x8000, v11
	global_load_lds_dwordx4 v[4:5], off
	v_add_u32_e32 v4, v238, v12
	v_ashrrev_i32_e32 v5, 31, v4
	v_lshlrev_b64 v[4:5], 11, v[4:5]
	v_readfirstlane_b32 s0, v1
	v_lshl_add_u64 v[2:3], v[2:3], 0, v[4:5]
	s_mov_b32 m0, s0
	s_load_dword s0, s[24:25], 0x0
	global_load_lds_dwordx4 v[2:3], off
	v_ashrrev_i32_e32 v1, 1, v0
	v_and_b32_e32 v234, 0xdf, v0
	v_lshrrev_b32_e32 v0, 3, v0
	s_waitcnt lgkmcnt(0)
	s_lshr_b32 s8, s0, 3
	v_and_b32_e32 v0, 4, v0
	s_movk_i32 s0, 0xff80
	v_lshrrev_b32_e32 v1, 8, v224
	v_mul_u32_u24_e32 v1, 0x60, v1
	v_add_u32_e32 v235, v1, v0
	v_readlane_b32 s0, v253, 25
	s_add_u32 s48, s0, s74
	v_readlane_b32 s0, v253, 26
	s_addc_u32 s49, s0, s75
	v_readlane_b32 s0, v254, 55
	s_add_u32 s50, s0, s74
	v_readlane_b32 s0, v254, 56
	s_addc_u32 s51, s0, s75
	s_mov_b32 s9, 0
	s_mov_b64 s[52:53], 0
	s_branch .LBB0_268

.LBB0_268:
	v_mov_b32_e32 v32, v224
	v_mov_b32_e32 v167, v236
	v_and_b32_e32 v0, 31, v32
	v_lshrrev_b32_e32 v1, 1, v32
	v_lshrrev_b32_e32 v1, 8, v32
	v_mul_u32_u24_e32 v1, 0x60, v1
	v_add_u32_e32 v0, v1, v0
	v_lshlrev_b32_e32 v178, 7, v0
	v_lshlrev_b32_e32 v0, 7, v32
	v_and_b32_e32 v180, 0x6f80, v0
	v_lshrrev_b32_e32 v0, 5, v32
	v_bfe_u32 v2, v32, 1, 3
	v_bfe_u32 v1, v32, 5, 1
	v_bitop3_b32 v0, v0, v2, 1 bitop3:0x6c
	v_lshlrev_b32_e32 v181, 4, v0
	v_bitop3_b32 v0, v1, v2, 2 bitop3:0x36
	v_lshlrev_b32_e32 v179, 4, v0
	v_bitop3_b32 v0, v1, v2, 4 bitop3:0x36
	v_ashrrev_i32_e32 v185, 3, v32
	v_add_u32_e32 v3, 0x200, v32
	v_add_u32_e32 v4, 0x400, v32
	v_add_u32_e32 v5, 0x600, v32
	v_lshlrev_b32_e32 v169, 4, v0
	v_bitop3_b32 v0, v1, v2, 6 bitop3:0x36
	v_mov_b32_e32 v166, v238
	s_movk_i32 s0, 0xff
	v_lshrrev_b32_e32 v33, 4, v32
	v_ashrrev_i32_e32 v184, 3, v3
	v_ashrrev_i32_e32 v183, 3, v4
	v_ashrrev_i32_e32 v182, 3, v5
	v_lshrrev_b32_e32 v173, 3, v32
	v_lshrrev_b32_e32 v172, 3, v3
	v_lshrrev_b32_e32 v171, 3, v4
	v_lshrrev_b32_e32 v170, 3, v5
	v_lshlrev_b32_e32 v168, 4, v0
	v_add_u32_e32 v0, v185, v167
	v_cmp_gt_i32_e32 vcc, s73, v32
	v_cmp_lt_i32_e64 s[0:1], s0, v32
	v_xor_b32_e32 v132, v33, v32
	v_lshlrev_b32_e32 v177, 4, v32
	v_lshlrev_b32_e32 v175, 4, v4
	v_ashrrev_i32_e32 v1, 31, v0
	v_add_u32_e32 v2, v184, v167
	v_add_u32_e32 v4, v183, v167
	v_add_u32_e32 v6, v182, v167
	v_add_u32_e32 v8, v173, v167
	v_add_u32_e32 v10, v172, v167
	v_add_u32_e32 v12, v171, v167
	v_add_u32_e32 v14, v170, v167
	v_add_u32_e32 v16, v185, v166
	v_add_u32_e32 v18, v184, v166
	v_add_u32_e32 v20, v183, v166
	v_add_u32_e32 v22, v182, v166
	v_add_u32_e32 v24, v173, v166
	v_add_u32_e32 v26, v172, v166
	v_add_u32_e32 v28, v171, v166
	v_add_u32_e32 v30, v170, v166
	v_bitop3_b32 v32, v33, 7, v32 bitop3:0x48
	v_lshlrev_b32_e32 v176, 4, v3
	v_lshlrev_b32_e32 v174, 4, v5
	v_ashrrev_i32_e32 v3, 31, v2
	v_ashrrev_i32_e32 v5, 31, v4
	v_ashrrev_i32_e32 v7, 31, v6
	v_ashrrev_i32_e32 v9, 31, v8
	v_ashrrev_i32_e32 v11, 31, v10
	v_ashrrev_i32_e32 v13, 31, v12
	v_ashrrev_i32_e32 v15, 31, v14
	v_lshlrev_b64 v[0:1], 11, v[0:1]
	v_ashrrev_i32_e32 v17, 31, v16
	v_ashrrev_i32_e32 v19, 31, v18
	v_ashrrev_i32_e32 v21, 31, v20
	v_ashrrev_i32_e32 v23, 31, v22
	v_ashrrev_i32_e32 v25, 31, v24
	v_ashrrev_i32_e32 v27, 31, v26
	v_ashrrev_i32_e32 v29, 31, v28
	v_ashrrev_i32_e32 v31, 31, v30
	v_lshlrev_b32_e32 v32, 4, v32
	s_waitcnt vmcnt(0)
	v_lshlrev_b64 v[2:3], 11, v[2:3]
	v_lshlrev_b64 v[4:5], 11, v[4:5]
	v_lshlrev_b64 v[6:7], 11, v[6:7]
	v_lshlrev_b64 v[8:9], 11, v[8:9]
	v_lshlrev_b64 v[10:11], 11, v[10:11]
	v_lshlrev_b64 v[12:13], 11, v[12:13]
	v_lshlrev_b64 v[14:15], 11, v[14:15]
	v_lshlrev_b64 v[16:17], 11, v[16:17]
	v_lshlrev_b64 v[18:19], 11, v[18:19]
	v_lshlrev_b64 v[20:21], 11, v[20:21]
	v_lshlrev_b64 v[22:23], 11, v[22:23]
	v_lshlrev_b64 v[24:25], 11, v[24:25]
	v_lshlrev_b64 v[26:27], 11, v[26:27]
	v_lshlrev_b64 v[28:29], 11, v[28:29]
	v_lshlrev_b64 v[30:31], 11, v[30:31]
	v_or_b32_e32 v0, v0, v32
	v_lshl_add_u64 v[134:135], s[48:49], 0, v[0:1]
	v_or_b32_e32 v2, v2, v32
	v_or_b32_e32 v4, v4, v32
	v_or_b32_e32 v6, v6, v32
	v_or_b32_e32 v16, v16, v32
	v_or_b32_e32 v18, v18, v32
	v_or_b32_e32 v20, v20, v32
	v_or_b32_e32 v22, v22, v32
	v_or_b32_e32 v8, v8, v32
	v_or_b32_e32 v10, v10, v32
	v_or_b32_e32 v12, v12, v32
	v_or_b32_e32 v14, v14, v32
	v_or_b32_e32 v24, v24, v32
	v_or_b32_e32 v26, v26, v32
	v_or_b32_e32 v28, v28, v32
	v_or_b32_e32 v30, v30, v32
	v_mov_b32_e32 v0, 0
	v_mov_b32_e32 v128, v237
	v_lshl_add_u64 v[136:137], s[48:49], 0, v[2:3]
	v_lshl_add_u64 v[138:139], s[48:49], 0, v[4:5]
	v_lshl_add_u64 v[140:141], s[48:49], 0, v[6:7]
	v_lshl_add_u64 v[142:143], s[50:51], 0, v[16:17]
	v_lshl_add_u64 v[144:145], s[50:51], 0, v[18:19]
	v_lshl_add_u64 v[146:147], s[50:51], 0, v[20:21]
	v_lshl_add_u64 v[148:149], s[50:51], 0, v[22:23]
	v_lshl_add_u64 v[150:151], s[48:49], 0, v[8:9]
	v_lshl_add_u64 v[152:153], s[48:49], 0, v[10:11]
	v_lshl_add_u64 v[154:155], s[48:49], 0, v[12:13]
	v_lshl_add_u64 v[156:157], s[48:49], 0, v[14:15]
	v_lshl_add_u64 v[158:159], s[50:51], 0, v[24:25]
	v_lshl_add_u64 v[160:161], s[50:51], 0, v[26:27]
	v_lshl_add_u64 v[162:163], s[50:51], 0, v[28:29]
	v_lshl_add_u64 v[164:165], s[50:51], 0, v[30:31]
	s_mov_b64 s[4:5], 0
	v_mov_b32_e32 v1, v0
	v_mov_b32_e32 v2, v0
	v_mov_b32_e32 v3, v0
	v_mov_b32_e32 v4, v0
	v_mov_b32_e32 v5, v0
	v_mov_b32_e32 v6, v0
	v_mov_b32_e32 v7, v0
	v_mov_b32_e32 v8, v0
	v_mov_b32_e32 v9, v0
	v_mov_b32_e32 v10, v0
	v_mov_b32_e32 v11, v0
	v_mov_b32_e32 v12, v0
	v_mov_b32_e32 v13, v0
	v_mov_b32_e32 v14, v0
	v_mov_b32_e32 v15, v0
	v_mov_b32_e32 v16, v0
	v_mov_b32_e32 v17, v0
	v_mov_b32_e32 v18, v0
	v_mov_b32_e32 v19, v0
	v_mov_b32_e32 v20, v0
	v_mov_b32_e32 v21, v0
	v_mov_b32_e32 v22, v0
	v_mov_b32_e32 v23, v0
	v_mov_b32_e32 v24, v0
	v_mov_b32_e32 v25, v0
	v_mov_b32_e32 v26, v0
	v_mov_b32_e32 v27, v0
	v_mov_b32_e32 v28, v0
	v_mov_b32_e32 v29, v0
	v_mov_b32_e32 v30, v0
	v_mov_b32_e32 v31, v0
	v_mov_b32_e32 v32, v0
	v_mov_b32_e32 v33, v0
	v_mov_b32_e32 v34, v0
	v_mov_b32_e32 v35, v0
	v_mov_b32_e32 v36, v0
	v_mov_b32_e32 v37, v0
	v_mov_b32_e32 v38, v0
	v_mov_b32_e32 v39, v0
	v_mov_b32_e32 v40, v0
	v_mov_b32_e32 v41, v0
	v_mov_b32_e32 v42, v0
	v_mov_b32_e32 v43, v0
	v_mov_b32_e32 v44, v0
	v_mov_b32_e32 v45, v0
	v_mov_b32_e32 v46, v0
	v_mov_b32_e32 v47, v0
	v_mov_b32_e32 v48, v0
	v_mov_b32_e32 v49, v0
	v_mov_b32_e32 v50, v0
	v_mov_b32_e32 v51, v0
	v_mov_b32_e32 v52, v0
	v_mov_b32_e32 v53, v0
	v_mov_b32_e32 v54, v0
	v_mov_b32_e32 v55, v0
	v_mov_b32_e32 v56, v0
	v_mov_b32_e32 v57, v0
	v_mov_b32_e32 v58, v0
	v_mov_b32_e32 v59, v0
	v_mov_b32_e32 v60, v0
	v_mov_b32_e32 v61, v0
	v_mov_b32_e32 v62, v0
	v_mov_b32_e32 v63, v0
	v_mov_b32_e32 v64, v0
	v_mov_b32_e32 v65, v0
	v_mov_b32_e32 v66, v0
	v_mov_b32_e32 v67, v0
	v_mov_b32_e32 v68, v0
	v_mov_b32_e32 v69, v0
	v_mov_b32_e32 v70, v0
	v_mov_b32_e32 v71, v0
	v_mov_b32_e32 v72, v0
	v_mov_b32_e32 v73, v0
	v_mov_b32_e32 v74, v0
	v_mov_b32_e32 v75, v0
	v_mov_b32_e32 v76, v0
	v_mov_b32_e32 v77, v0
	v_mov_b32_e32 v78, v0
	v_mov_b32_e32 v79, v0
	v_mov_b32_e32 v80, v0
	v_mov_b32_e32 v81, v0
	v_mov_b32_e32 v82, v0
	v_mov_b32_e32 v83, v0
	v_mov_b32_e32 v84, v0
	v_mov_b32_e32 v85, v0
	v_mov_b32_e32 v86, v0
	v_mov_b32_e32 v87, v0
	v_mov_b32_e32 v88, v0
	v_mov_b32_e32 v89, v0
	v_mov_b32_e32 v90, v0
	v_mov_b32_e32 v91, v0
	v_mov_b32_e32 v92, v0
	v_mov_b32_e32 v93, v0
	v_mov_b32_e32 v94, v0
	v_mov_b32_e32 v95, v0
	v_mov_b32_e32 v96, v0
	v_mov_b32_e32 v97, v0
	v_mov_b32_e32 v98, v0
	v_mov_b32_e32 v99, v0
	v_mov_b32_e32 v100, v0
	v_mov_b32_e32 v101, v0
	v_mov_b32_e32 v102, v0
	v_mov_b32_e32 v103, v0
	v_mov_b32_e32 v104, v0
	v_mov_b32_e32 v105, v0
	v_mov_b32_e32 v106, v0
	v_mov_b32_e32 v107, v0
	v_mov_b32_e32 v108, v0
	v_mov_b32_e32 v109, v0
	v_mov_b32_e32 v110, v0
	v_mov_b32_e32 v111, v0
	v_mov_b32_e32 v112, v0
	v_mov_b32_e32 v113, v0
	v_mov_b32_e32 v114, v0
	v_mov_b32_e32 v115, v0
	v_mov_b32_e32 v116, v0
	v_mov_b32_e32 v117, v0
	v_mov_b32_e32 v118, v0
	v_mov_b32_e32 v119, v0
	v_mov_b32_e32 v120, v0
	v_mov_b32_e32 v121, v0
	v_mov_b32_e32 v122, v0
	v_mov_b32_e32 v123, v0
	v_mov_b32_e32 v124, v0
	v_mov_b32_e32 v125, v0
	v_mov_b32_e32 v126, v0
	v_mov_b32_e32 v127, v0
	s_waitcnt vmcnt(0)
	s_barrier
	s_lshl_b32 s13, s9, 16
	s_and_saveexec_b64 s[6:7], vcc
	s_cbranch_execz .LBB0_271
	s_branch .LBB0_270

.LBB0_270:
	s_xor_b32 s14, s13, 0x10000
	s_add_i32 s14, s14, 0
	v_add_u32_e32 v133, s14, v177
	v_add_u32_e32 v186, s14, v176
	v_readfirstlane_b32 s15, v133
	v_lshl_add_u64 v[130:131], v[134:135], 0, s[4:5]
	s_mov_b32 m0, s15
	v_readfirstlane_b32 s15, v186
	v_add_u32_e32 v187, s14, v175
	global_load_lds_dwordx4 v[130:131], off
	v_lshl_add_u64 v[130:131], v[136:137], 0, s[4:5]
	s_mov_b32 m0, s15
	v_readfirstlane_b32 s15, v187
	v_add_u32_e32 v188, s14, v174
	global_load_lds_dwordx4 v[130:131], off
	v_lshl_add_u64 v[130:131], v[138:139], 0, s[4:5]
	s_mov_b32 m0, s15
	v_readfirstlane_b32 s14, v188
	v_add_u32_e32 v133, 0x8000, v133
	global_load_lds_dwordx4 v[130:131], off
	v_readfirstlane_b32 s14, v133
	v_add_u32_e32 v133, 0x8000, v186
	v_lshl_add_u64 v[130:131], v[142:143], 0, s[4:5]
	s_mov_b32 m0, s14
	v_readfirstlane_b32 s14, v133
	v_add_u32_e32 v133, 0x8000, v187
	global_load_lds_dwordx4 v[130:131], off
	v_lshl_add_u64 v[130:131], v[144:145], 0, s[4:5]
	s_mov_b32 m0, s14
	v_readfirstlane_b32 s14, v133
	v_add_u32_e32 v133, 0x8000, v188
	global_load_lds_dwordx4 v[130:131], off
	v_lshl_add_u64 v[130:131], v[146:147], 0, s[4:5]
	s_mov_b32 m0, s14
	v_readfirstlane_b32 s14, v133
	global_load_lds_dwordx4 v[130:131], off
	v_lshl_add_u64 v[130:131], v[148:149], 0, s[4:5]
	s_mov_b32 m0, s14
	s_nop 0
	global_load_lds_dwordx4 v[130:131], off
.LBB0_271:
	s_or_b64 exec, exec, s[6:7]
	s_add_i32 s6, s13, 0
	v_add_u32_e32 v131, s6, v178
	v_add_u32_e32 v133, v131, v181
	v_add_u32_e32 v130, s6, v180
	ds_read_b128 v[186:189], v133
	ds_read_b128 v[190:193], v133 offset:4096
	ds_read_b128 v[194:197], v133 offset:8192
	v_add_u32_e32 v133, v130, v181
	ds_read_b128 v[202:205], v133 offset:32768
	ds_read_b128 v[206:209], v133 offset:36864
	s_setprio 1
	s_waitcnt lgkmcnt(0)
	v_mfma_f32_32x32x16_bf16 v[112:127], v[186:189], v[202:205], v[112:127]
	v_mfma_f32_32x32x16_bf16 v[96:111], v[186:189], v[206:209], v[96:111]
	v_mfma_f32_32x32x16_bf16 v[80:95], v[190:193], v[202:205], v[80:95]
	v_mfma_f32_32x32x16_bf16 v[64:79], v[190:193], v[206:209], v[64:79]
	v_mfma_f32_32x32x16_bf16 v[48:63], v[194:197], v[202:205], v[48:63]
	v_mfma_f32_32x32x16_bf16 v[32:47], v[194:197], v[206:209], v[32:47]
	s_setprio 0
	v_add_u32_e32 v133, v131, v179
	ds_read_b128 v[186:189], v133
	ds_read_b128 v[190:193], v133 offset:4096
	ds_read_b128 v[194:197], v133 offset:8192
	v_add_u32_e32 v133, v130, v179
	ds_read_b128 v[202:205], v133 offset:32768
	ds_read_b128 v[206:209], v133 offset:36864
	s_setprio 1
	s_waitcnt lgkmcnt(0)
	v_mfma_f32_32x32x16_bf16 v[112:127], v[186:189], v[202:205], v[112:127]
	v_mfma_f32_32x32x16_bf16 v[96:111], v[186:189], v[206:209], v[96:111]
	v_mfma_f32_32x32x16_bf16 v[80:95], v[190:193], v[202:205], v[80:95]
	v_mfma_f32_32x32x16_bf16 v[64:79], v[190:193], v[206:209], v[64:79]
	v_mfma_f32_32x32x16_bf16 v[48:63], v[194:197], v[202:205], v[48:63]
	v_mfma_f32_32x32x16_bf16 v[32:47], v[194:197], v[206:209], v[32:47]
	s_setprio 0
	s_and_saveexec_b64 s[6:7], s[0:1]
	s_cbranch_execz .LBB0_273
	s_xor_b32 s13, s13, 0x10000
	s_add_i32 s13, s13, 0
	v_add_u32_e32 v133, s13, v177
	v_add_u32_e32 v188, s13, v176
	v_readfirstlane_b32 s14, v133
	v_lshl_add_u64 v[186:187], v[150:151], 0, s[4:5]
	s_mov_b32 m0, s14
	v_readfirstlane_b32 s14, v188
	v_add_u32_e32 v189, s13, v175
	global_load_lds_dwordx4 v[186:187], off
	v_lshl_add_u64 v[186:187], v[152:153], 0, s[4:5]
	s_mov_b32 m0, s14
	v_readfirstlane_b32 s14, v189
	v_add_u32_e32 v190, s13, v174
	global_load_lds_dwordx4 v[186:187], off
	v_lshl_add_u64 v[186:187], v[154:155], 0, s[4:5]
	s_mov_b32 m0, s14
	v_readfirstlane_b32 s13, v190
	v_add_u32_e32 v133, 0x8000, v133
	global_load_lds_dwordx4 v[186:187], off
	v_readfirstlane_b32 s13, v133
	v_add_u32_e32 v133, 0x8000, v188
	v_lshl_add_u64 v[186:187], v[158:159], 0, s[4:5]
	s_mov_b32 m0, s13
	v_readfirstlane_b32 s13, v133
	v_add_u32_e32 v133, 0x8000, v189
	global_load_lds_dwordx4 v[186:187], off
	v_lshl_add_u64 v[186:187], v[160:161], 0, s[4:5]
	s_mov_b32 m0, s13
	v_readfirstlane_b32 s13, v133
	v_add_u32_e32 v133, 0x8000, v190
	global_load_lds_dwordx4 v[186:187], off
	v_lshl_add_u64 v[186:187], v[162:163], 0, s[4:5]
	s_mov_b32 m0, s13
	v_readfirstlane_b32 s13, v133
	global_load_lds_dwordx4 v[186:187], off
	v_lshl_add_u64 v[186:187], v[164:165], 0, s[4:5]
	s_mov_b32 m0, s13
	s_nop 0
	global_load_lds_dwordx4 v[186:187], off
.LBB0_273:
	s_or_b64 exec, exec, s[6:7]
	v_add_u32_e32 v133, v131, v169
	ds_read_b128 v[186:189], v133
	ds_read_b128 v[190:193], v133 offset:4096
	ds_read_b128 v[194:197], v133 offset:8192
	v_add_u32_e32 v133, v130, v169
	ds_read_b128 v[202:205], v133 offset:32768
	ds_read_b128 v[206:209], v133 offset:36864
	s_setprio 1
	s_waitcnt lgkmcnt(0)
	v_mfma_f32_32x32x16_bf16 v[112:127], v[186:189], v[202:205], v[112:127]
	v_mfma_f32_32x32x16_bf16 v[96:111], v[186:189], v[206:209], v[96:111]
	v_mfma_f32_32x32x16_bf16 v[80:95], v[190:193], v[202:205], v[80:95]
	v_mfma_f32_32x32x16_bf16 v[64:79], v[190:193], v[206:209], v[64:79]
	v_mfma_f32_32x32x16_bf16 v[48:63], v[194:197], v[202:205], v[48:63]
	v_mfma_f32_32x32x16_bf16 v[32:47], v[194:197], v[206:209], v[32:47]
	s_setprio 0
	v_add_u32_e32 v131, v131, v168
	ds_read_b128 v[186:189], v131
	ds_read_b128 v[190:193], v131 offset:4096
	ds_read_b128 v[194:197], v131 offset:8192
	v_add_u32_e32 v130, v130, v168
	ds_read_b128 v[202:205], v130 offset:32768
	ds_read_b128 v[206:209], v130 offset:36864
	s_setprio 1
	s_waitcnt lgkmcnt(0)
	v_mfma_f32_32x32x16_bf16 v[112:127], v[186:189], v[202:205], v[112:127]
	v_mfma_f32_32x32x16_bf16 v[96:111], v[186:189], v[206:209], v[96:111]
	v_mfma_f32_32x32x16_bf16 v[80:95], v[190:193], v[202:205], v[80:95]
	v_mfma_f32_32x32x16_bf16 v[64:79], v[190:193], v[206:209], v[64:79]
	v_mfma_f32_32x32x16_bf16 v[48:63], v[194:197], v[202:205], v[48:63]
	v_mfma_f32_32x32x16_bf16 v[32:47], v[194:197], v[206:209], v[32:47]
	s_setprio 0
	s_xor_b32 s6, s9, 1
	s_waitcnt vmcnt(0)
	s_add_u32 s4, s4, 0x80
	s_addc_u32 s5, s5, 0
	s_cmpk_lg_i32 s4, 0x780
	s_waitcnt vmcnt(0)
	s_barrier
	s_cbranch_scc1 .LBB0_269
	v_add_u32_e32 v237, s8, v128
	v_cmp_lt_i32_e64 s[36:37], 31, v237
	s_xor_b64 s[0:1], vcc, -1
	s_nor_b64 s[0:1], s[0:1], s[36:37]
	v_cndmask_b32_e64 v128, v237, v128, s[36:37]
	v_ashrrev_i32_e32 v130, 31, v128
	v_lshrrev_b32_e32 v130, 30, v130
	v_add_u32_e32 v130, v128, v130
	v_lshrrev_b32_e32 v131, 2, v130
	v_and_b32_e32 v130, 0xfffffc, v130
	v_sub_u32_e32 v130, v128, v130
	v_lshlrev_b32_e32 v128, 4, v132
	v_and_b32_e32 v128, 0x70, v128
	v_add_lshl_u32 v236, v131, v233, 8
	v_lshl_add_u64 v[136:137], s[44:45], 0, v[128:129]
	v_lshl_add_u64 v[134:135], s[46:47], 0, v[128:129]
	v_lshlrev_b32_e32 v238, 8, v130
	s_and_saveexec_b64 s[14:15], s[0:1]
	s_xor_b64 s[0:1], exec, s[14:15]
	s_cbranch_execz .LBB0_276
	s_lshl_b32 s4, s6, 16
	s_xor_b32 s5, s4, 0x10000
	v_add_u32_e32 v130, v236, v185
	s_add_i32 s5, s5, 0
	v_ashrrev_i32_e32 v131, 31, v130
	v_add_u32_e32 v132, v184, v236
	v_add_u32_e32 v128, s5, v177
	v_lshlrev_b64 v[130:131], 11, v[130:131]
	v_ashrrev_i32_e32 v133, 31, v132
	v_readfirstlane_b32 s7, v128
	v_add_u32_e32 v142, s5, v176
	v_lshl_add_u64 v[130:131], v[136:137], 0, v[130:131]
	v_lshlrev_b64 v[132:133], 11, v[132:133]
	s_mov_b32 m0, s7
	v_readfirstlane_b32 s7, v142
	v_lshl_add_u64 v[132:133], v[136:137], 0, v[132:133]
	v_add_u32_e32 v138, v183, v236
	global_load_lds_dwordx4 v[130:131], off
	s_mov_b32 m0, s7
	v_ashrrev_i32_e32 v139, 31, v138
	v_add_u32_e32 v140, v182, v236
	global_load_lds_dwordx4 v[132:133], off
	v_add_u32_e32 v132, s5, v175
	v_lshlrev_b64 v[138:139], 11, v[138:139]
	v_ashrrev_i32_e32 v141, 31, v140
	v_readfirstlane_b32 s7, v132
	v_add_u32_e32 v133, s5, v174
	v_add_u32_e32 v130, v238, v185
	v_lshl_add_u64 v[138:139], v[136:137], 0, v[138:139]
	v_lshlrev_b64 v[140:141], 11, v[140:141]
	s_mov_b32 m0, s7
	v_readfirstlane_b32 s5, v133
	v_ashrrev_i32_e32 v131, 31, v130
	v_add_u32_e32 v128, 0x8000, v128
	v_lshl_add_u64 v[140:141], v[136:137], 0, v[140:141]
	global_load_lds_dwordx4 v[138:139], off
	s_mov_b32 m0, s5
	v_lshlrev_b64 v[130:131], 11, v[130:131]
	v_readfirstlane_b32 s5, v128
	global_load_lds_dwordx4 v[140:141], off
	v_lshl_add_u64 v[130:131], v[134:135], 0, v[130:131]
	s_mov_b32 m0, s5
	v_add_u32_e32 v128, 0x8000, v142
	global_load_lds_dwordx4 v[130:131], off
	v_add_u32_e32 v130, v184, v238
	v_ashrrev_i32_e32 v131, 31, v130
	v_lshlrev_b64 v[130:131], 11, v[130:131]
	v_readfirstlane_b32 s5, v128
	v_lshl_add_u64 v[130:131], v[134:135], 0, v[130:131]
	s_mov_b32 m0, s5
	v_add_u32_e32 v128, 0x8000, v132
	global_load_lds_dwordx4 v[130:131], off
	v_add_u32_e32 v130, v183, v238
	v_ashrrev_i32_e32 v131, 31, v130
	v_lshlrev_b64 v[130:131], 11, v[130:131]
	v_readfirstlane_b32 s5, v128
	v_lshl_add_u64 v[130:131], v[134:135], 0, v[130:131]
	s_mov_b32 m0, s5
	v_add_u32_e32 v128, 0x8000, v133
	global_load_lds_dwordx4 v[130:131], off
	v_add_u32_e32 v130, v182, v238
	v_ashrrev_i32_e32 v131, 31, v130
	v_lshlrev_b64 v[130:131], 11, v[130:131]
	v_readfirstlane_b32 s5, v128
	v_lshl_add_u64 v[130:131], v[134:135], 0, v[130:131]
	s_mov_b32 m0, s5
	s_nop 0
	global_load_lds_dwordx4 v[130:131], off
.LBB0_276:
	s_or_saveexec_b64 s[0:1], s[0:1]
	v_mov_b32_e32 v131, s4
	s_xor_b64 exec, exec, s[0:1]
	s_lshl_b32 s4, s6, 16
	v_mov_b32_e32 v131, s4
	s_or_b64 exec, exec, s[0:1]
	v_add_u32_e32 v128, 0, v131
	v_add_u32_e32 v130, v128, v178
	v_add_u32_e32 v132, v130, v181
	v_add_u32_e32 v128, v128, v180
	ds_read_b128 v[138:141], v132
	ds_read_b128 v[142:145], v132 offset:4096
	ds_read_b128 v[146:149], v132 offset:8192
	v_add_u32_e32 v132, v128, v181
	ds_read_b128 v[154:157], v132 offset:32768
	ds_read_b128 v[158:161], v132 offset:36864
	s_setprio 1
	s_waitcnt lgkmcnt(0)
	v_mfma_f32_32x32x16_bf16 v[112:127], v[138:141], v[154:157], v[112:127]
	v_mfma_f32_32x32x16_bf16 v[96:111], v[138:141], v[158:161], v[96:111]
	v_mfma_f32_32x32x16_bf16 v[80:95], v[142:145], v[154:157], v[80:95]
	v_mfma_f32_32x32x16_bf16 v[64:79], v[142:145], v[158:161], v[64:79]
	v_mfma_f32_32x32x16_bf16 v[48:63], v[146:149], v[154:157], v[48:63]
	v_mfma_f32_32x32x16_bf16 v[32:47], v[146:149], v[158:161], v[32:47]
	s_setprio 0
	v_add_u32_e32 v132, v130, v179
	ds_read_b128 v[138:141], v132
	ds_read_b128 v[142:145], v132 offset:4096
	ds_read_b128 v[146:149], v132 offset:8192
	v_add_u32_e32 v132, v128, v179
	ds_read_b128 v[154:157], v132 offset:32768
	ds_read_b128 v[158:161], v132 offset:36864
	s_setprio 1
	s_waitcnt lgkmcnt(0)
	v_mfma_f32_32x32x16_bf16 v[112:127], v[138:141], v[154:157], v[112:127]
	v_mfma_f32_32x32x16_bf16 v[96:111], v[138:141], v[158:161], v[96:111]
	v_mfma_f32_32x32x16_bf16 v[80:95], v[142:145], v[154:157], v[80:95]
	v_mfma_f32_32x32x16_bf16 v[64:79], v[142:145], v[158:161], v[64:79]
	v_mfma_f32_32x32x16_bf16 v[48:63], v[146:149], v[154:157], v[48:63]
	v_mfma_f32_32x32x16_bf16 v[32:47], v[146:149], v[158:161], v[32:47]
	s_setprio 0
	s_nor_b64 s[4:5], vcc, s[36:37]
	s_and_saveexec_b64 s[0:1], s[4:5]
	s_cbranch_execz .LBB0_280
	v_add_u32_e32 v132, v170, v236
	v_add_u32_e32 v138, v236, v173
	v_add_u32_e32 v140, v172, v236
	v_add_u32_e32 v142, v171, v236
	v_ashrrev_i32_e32 v133, 31, v132
	v_ashrrev_i32_e32 v139, 31, v138
	v_ashrrev_i32_e32 v141, 31, v140
	v_ashrrev_i32_e32 v143, 31, v142
	v_xor_b32_e32 v131, 0x10000, v131
	v_lshlrev_b64 v[132:133], 11, v[132:133]
	v_lshlrev_b64 v[138:139], 11, v[138:139]
	v_lshlrev_b64 v[140:141], 11, v[140:141]
	v_lshlrev_b64 v[142:143], 11, v[142:143]
	v_add_u32_e32 v131, 0, v131
	v_lshl_add_u64 v[132:133], v[136:137], 0, v[132:133]
	v_lshl_add_u64 v[138:139], v[136:137], 0, v[138:139]
	v_lshl_add_u64 v[140:141], v[136:137], 0, v[140:141]
	v_lshl_add_u64 v[136:137], v[136:137], 0, v[142:143]
	v_add_u32_e32 v142, v131, v177
	s_nop 0
	v_readfirstlane_b32 s4, v142
	s_mov_b32 m0, s4
	s_nop 0
	global_load_lds_dwordx4 v[138:139], off
	v_add_u32_e32 v138, v131, v176
	v_add_u32_e32 v139, v131, v175
	v_readfirstlane_b32 s4, v138
	s_mov_b32 m0, s4
	v_readfirstlane_b32 s4, v139
	v_add_u32_e32 v131, v131, v174
	global_load_lds_dwordx4 v[140:141], off
	s_mov_b32 m0, s4
	v_readfirstlane_b32 s4, v131
	global_load_lds_dwordx4 v[136:137], off
	s_mov_b32 m0, s4
	v_add_u32_e32 v136, 0x8000, v142
	global_load_lds_dwordx4 v[132:133], off
	v_add_u32_e32 v132, v238, v173
	v_ashrrev_i32_e32 v133, 31, v132
	v_lshlrev_b64 v[132:133], 11, v[132:133]
	v_readfirstlane_b32 s4, v136
	v_lshl_add_u64 v[132:133], v[134:135], 0, v[132:133]
	s_mov_b32 m0, s4
	v_add_u32_e32 v136, 0x8000, v138
	global_load_lds_dwordx4 v[132:133], off
	v_add_u32_e32 v132, v172, v238
	v_ashrrev_i32_e32 v133, 31, v132
	v_lshlrev_b64 v[132:133], 11, v[132:133]
	v_readfirstlane_b32 s4, v136
	v_lshl_add_u64 v[132:133], v[134:135], 0, v[132:133]
	s_mov_b32 m0, s4
	v_add_u32_e32 v136, 0x8000, v139
	global_load_lds_dwordx4 v[132:133], off
	v_add_u32_e32 v132, v171, v238
	v_ashrrev_i32_e32 v133, 31, v132
	v_lshlrev_b64 v[132:133], 11, v[132:133]
	v_readfirstlane_b32 s4, v136
	v_lshl_add_u64 v[132:133], v[134:135], 0, v[132:133]
	s_mov_b32 m0, s4
	v_add_u32_e32 v131, 0x8000, v131
	global_load_lds_dwordx4 v[132:133], off
	v_add_u32_e32 v132, v170, v238
	v_ashrrev_i32_e32 v133, 31, v132
	v_lshlrev_b64 v[132:133], 11, v[132:133]
	v_readfirstlane_b32 s4, v131
	v_lshl_add_u64 v[132:133], v[134:135], 0, v[132:133]
	s_mov_b32 m0, s4
	s_nop 0
	global_load_lds_dwordx4 v[132:133], off
.LBB0_280:
	s_or_b64 exec, exec, s[0:1]
	v_add_u32_e32 v222, v167, v235
	v_or_b32_e32 v223, v166, v234
	v_lshlrev_b32_e32 v221, 12, v222
	v_lshl_add_u32 v221, v223, 2, v221
	v_readfirstlane_b32 s4, v222
	s_nop 3
	s_mov_b64 s[38:39], s[68:69]
	s_and_b64 vcc, exec, s[18:19]
	s_cbranch_vccnz .Lg4s0_done
	s_add_i32 s0, s4, 0
	s_cmp_lt_i32 s0, s33
	s_cselect_b32 s38, s76, s78
	s_cselect_b32 s39, s77, s79
	s_cbranch_scc1 .Lg4s0_done
	s_sub_u32 s38, s38, 0x2000000
	s_subb_u32 s39, s39, 0
.Lg4s0_done:
	s_mov_b32 s0, s38
	s_mov_b32 s1, s39
	global_load_dword v189, v221, s[0:1]
	global_load_dword v205, v221, s[0:1] offset:128
	s_add_u32 s0, s38, 0x1000
	s_addc_u32 s1, s39, 0
	global_load_dword v190, v221, s[0:1]
	global_load_dword v206, v221, s[0:1] offset:128
	s_add_u32 s0, s38, 0x2000
	s_addc_u32 s1, s39, 0
	global_load_dword v191, v221, s[0:1]
	global_load_dword v207, v221, s[0:1] offset:128
	s_add_u32 s0, s38, 0x3000
	s_addc_u32 s1, s39, 0
	global_load_dword v192, v221, s[0:1]
	global_load_dword v208, v221, s[0:1] offset:128
	s_add_u32 s0, s38, 0x8000
	s_addc_u32 s1, s39, 0
	global_load_dword v193, v221, s[0:1]
	global_load_dword v209, v221, s[0:1] offset:128
	s_add_u32 s0, s38, 0x9000
	s_addc_u32 s1, s39, 0
	global_load_dword v194, v221, s[0:1]
	global_load_dword v210, v221, s[0:1] offset:128
	s_add_u32 s0, s38, 0xa000
	s_addc_u32 s1, s39, 0
	global_load_dword v195, v221, s[0:1]
	global_load_dword v211, v221, s[0:1] offset:128
	s_add_u32 s0, s38, 0xb000
	s_addc_u32 s1, s39, 0
	global_load_dword v196, v221, s[0:1]
	global_load_dword v212, v221, s[0:1] offset:128
	s_add_u32 s0, s38, 0x10000
	s_addc_u32 s1, s39, 0
	global_load_dword v197, v221, s[0:1]
	global_load_dword v213, v221, s[0:1] offset:128
	s_add_u32 s0, s38, 0x11000
	s_addc_u32 s1, s39, 0
	global_load_dword v198, v221, s[0:1]
	global_load_dword v214, v221, s[0:1] offset:128
	s_add_u32 s0, s38, 0x12000
	s_addc_u32 s1, s39, 0
	global_load_dword v199, v221, s[0:1]
	global_load_dword v215, v221, s[0:1] offset:128
	s_add_u32 s0, s38, 0x13000
	s_addc_u32 s1, s39, 0
	global_load_dword v200, v221, s[0:1]
	global_load_dword v216, v221, s[0:1] offset:128
	s_add_u32 s0, s38, 0x18000
	s_addc_u32 s1, s39, 0
	global_load_dword v201, v221, s[0:1]
	global_load_dword v217, v221, s[0:1] offset:128
	s_add_u32 s0, s38, 0x19000
	s_addc_u32 s1, s39, 0
	global_load_dword v202, v221, s[0:1]
	global_load_dword v218, v221, s[0:1] offset:128
	s_add_u32 s0, s38, 0x1a000
	s_addc_u32 s1, s39, 0
	global_load_dword v203, v221, s[0:1]
	global_load_dword v219, v221, s[0:1] offset:128
	s_add_u32 s0, s38, 0x1b000
	s_addc_u32 s1, s39, 0
	global_load_dword v204, v221, s[0:1]
	global_load_dword v220, v221, s[0:1] offset:128
	v_add_u32_e32 v131, v130, v169
	ds_read_b128 v[132:135], v131
	ds_read_b128 v[136:139], v131 offset:4096
	ds_read_b128 v[140:143], v131 offset:8192
	v_add_u32_e32 v131, v128, v169
	ds_read_b128 v[148:151], v131 offset:32768
	ds_read_b128 v[152:155], v131 offset:36864
	s_setprio 1
	s_waitcnt lgkmcnt(0)
	v_mfma_f32_32x32x16_bf16 v[112:127], v[132:135], v[148:151], v[112:127]
	v_mfma_f32_32x32x16_bf16 v[96:111], v[132:135], v[152:155], v[96:111]
	v_mfma_f32_32x32x16_bf16 v[80:95], v[136:139], v[148:151], v[80:95]
	v_mfma_f32_32x32x16_bf16 v[64:79], v[136:139], v[152:155], v[64:79]
	v_mfma_f32_32x32x16_bf16 v[48:63], v[140:143], v[148:151], v[48:63]
	v_mfma_f32_32x32x16_bf16 v[32:47], v[140:143], v[152:155], v[32:47]
	s_setprio 0
	v_add_u32_e32 v142, v130, v168
	ds_read_b128 v[130:133], v142
	ds_read_b128 v[134:137], v142 offset:4096
	ds_read_b128 v[138:141], v142 offset:8192
	v_add_u32_e32 v128, v128, v168
	ds_read_b128 v[146:149], v128 offset:32768
	ds_read_b128 v[150:153], v128 offset:36864
	s_setprio 1
	s_waitcnt lgkmcnt(0)
	v_mfma_f32_32x32x16_bf16 v[112:127], v[130:133], v[146:149], v[112:127]
	v_mfma_f32_32x32x16_bf16 v[96:111], v[130:133], v[150:153], v[96:111]
	v_mfma_f32_32x32x16_bf16 v[80:95], v[134:137], v[146:149], v[80:95]
	v_mfma_f32_32x32x16_bf16 v[64:79], v[134:137], v[150:153], v[64:79]
	v_mfma_f32_32x32x16_bf16 v[48:63], v[138:141], v[146:149], v[48:63]
	v_mfma_f32_32x32x16_bf16 v[32:47], v[138:141], v[150:153], v[32:47]
	s_setprio 0
	v_or_b32_e32 v134, v166, v234
	v_readlane_b32 s1, v254, 62
	s_movk_i32 s0, 0x6000
	v_lshlrev_b32_e32 v134, 2, v134
	v_add_u32_e32 v222, v167, v235
	v_add_u32_e32 v134, 0x2000, v134
	v_mov_b32_e32 v135, 0
	v_add_u32_e32 v132, 0xffffe000, v222
	v_ashrrev_i32_e32 v132, 10, v132
	v_add_u32_e32 v132, 1, v132
	v_max_i32_e32 v132, 0, v132
	v_add_u32_e32 v132, s1, v132
	v_mov_b64_e32 v[130:131], s[66:67]
	v_mad_u64_u32 v[130:131], vcc, v132, s0, v[130:131]
	v_lshl_add_u64 v[130:131], v[130:131], 0, v[134:135]
	global_load_dword v128, v[130:131], off
	global_load_dword v133, v[130:131], off offset:128
	v_add_u32_e32 v132, 0xffffe020, v222
	v_ashrrev_i32_e32 v132, 10, v132
	v_add_u32_e32 v132, 1, v132
	v_max_i32_e32 v132, 0, v132
	v_add_u32_e32 v132, s1, v132
	v_mov_b64_e32 v[130:131], s[66:67]
	v_mad_u64_u32 v[130:131], vcc, v132, s0, v[130:131]
	v_lshl_add_u64 v[130:131], v[130:131], 0, v[134:135]
	global_load_dword v142, v[130:131], off
	global_load_dword v143, v[130:131], off offset:128
	v_add_u32_e32 v132, 0xffffe040, v222
	v_ashrrev_i32_e32 v132, 10, v132
	v_add_u32_e32 v132, 1, v132
	v_max_i32_e32 v132, 0, v132
	v_add_u32_e32 v132, s1, v132
	v_mov_b64_e32 v[130:131], s[66:67]
	v_mad_u64_u32 v[130:131], vcc, v132, s0, v[130:131]
	v_lshl_add_u64 v[130:131], v[130:131], 0, v[134:135]
	global_load_dword v144, v[130:131], off
	global_load_dword v145, v[130:131], off offset:128
	s_mov_b64 s[38:39], s[68:69]
	s_and_b64 vcc, exec, s[18:19]
	s_cbranch_vccnz .Lg4s1_done
	s_add_i32 s0, s4, 32
	s_cmp_lt_i32 s0, s33
	s_cselect_b32 s38, s76, s78
	s_cselect_b32 s39, s77, s79
	s_cbranch_scc1 .Lg4s1_done
	s_sub_u32 s38, s38, 0x2000000
	s_subb_u32 s39, s39, 0
.Lg4s1_done:
	s_add_u32 s0, s38, 0x20000
	s_addc_u32 s1, s39, 0
	global_load_dword v150, v221, s[0:1]
	global_load_dword v172, v221, s[0:1] offset:128
	s_add_u32 s0, s38, 0x21000
	s_addc_u32 s1, s39, 0
	global_load_dword v151, v221, s[0:1]
	global_load_dword v173, v221, s[0:1] offset:128
	s_add_u32 s0, s38, 0x22000
	s_addc_u32 s1, s39, 0
	global_load_dword v152, v221, s[0:1]
	global_load_dword v174, v221, s[0:1] offset:128
	s_add_u32 s0, s38, 0x23000
	s_addc_u32 s1, s39, 0
	global_load_dword v153, v221, s[0:1]
	global_load_dword v175, v221, s[0:1] offset:128
	s_add_u32 s0, s38, 0x28000
	s_addc_u32 s1, s39, 0
	global_load_dword v154, v221, s[0:1]
	global_load_dword v176, v221, s[0:1] offset:128
	s_add_u32 s0, s38, 0x29000
	s_addc_u32 s1, s39, 0
	global_load_dword v155, v221, s[0:1]
	global_load_dword v177, v221, s[0:1] offset:128
	s_add_u32 s0, s38, 0x2a000
	s_addc_u32 s1, s39, 0
	global_load_dword v156, v221, s[0:1]
	global_load_dword v178, v221, s[0:1] offset:128
	s_add_u32 s0, s38, 0x2b000
	s_addc_u32 s1, s39, 0
	global_load_dword v157, v221, s[0:1]
	global_load_dword v179, v221, s[0:1] offset:128
	s_add_u32 s0, s38, 0x30000
	s_addc_u32 s1, s39, 0
	global_load_dword v158, v221, s[0:1]
	global_load_dword v180, v221, s[0:1] offset:128
	s_add_u32 s0, s38, 0x31000
	s_addc_u32 s1, s39, 0
	global_load_dword v159, v221, s[0:1]
	global_load_dword v181, v221, s[0:1] offset:128
	s_add_u32 s0, s38, 0x32000
	s_addc_u32 s1, s39, 0
	global_load_dword v160, v221, s[0:1]
	global_load_dword v182, v221, s[0:1] offset:128
	s_add_u32 s0, s38, 0x33000
	s_addc_u32 s1, s39, 0
	global_load_dword v161, v221, s[0:1]
	global_load_dword v183, v221, s[0:1] offset:128
	s_add_u32 s0, s38, 0x38000
	s_addc_u32 s1, s39, 0
	global_load_dword v162, v221, s[0:1]
	global_load_dword v184, v221, s[0:1] offset:128
	s_add_u32 s0, s38, 0x39000
	s_addc_u32 s1, s39, 0
	global_load_dword v163, v221, s[0:1]
	global_load_dword v185, v221, s[0:1] offset:128
	s_add_u32 s0, s38, 0x3a000
	s_addc_u32 s1, s39, 0
	global_load_dword v164, v221, s[0:1]
	global_load_dword v186, v221, s[0:1] offset:128
	s_add_u32 s0, s38, 0x3b000
	s_addc_u32 s1, s39, 0
	global_load_dword v165, v221, s[0:1]
	global_load_dword v187, v221, s[0:1] offset:128
	s_waitcnt vmcnt(32)
	v_fmac_f32_e32 v189, v112, v128
	v_fmac_f32_e32 v190, v113, v128
	v_fmac_f32_e32 v191, v114, v128
	v_fmac_f32_e32 v192, v115, v128
	v_fmac_f32_e32 v193, v116, v128
	v_fmac_f32_e32 v194, v117, v128
	v_fmac_f32_e32 v195, v118, v128
	v_fmac_f32_e32 v196, v119, v128
	v_fmac_f32_e32 v197, v120, v128
	v_fmac_f32_e32 v198, v121, v128
	v_fmac_f32_e32 v199, v122, v128
	v_fmac_f32_e32 v200, v123, v128
	v_fmac_f32_e32 v201, v124, v128
	v_fmac_f32_e32 v202, v125, v128
	v_fmac_f32_e32 v203, v126, v128
	v_fmac_f32_e32 v204, v127, v128
	v_fmac_f32_e32 v205, v96, v133
	v_fmac_f32_e32 v206, v97, v133
	v_fmac_f32_e32 v207, v98, v133
	v_fmac_f32_e32 v208, v99, v133
	v_fmac_f32_e32 v209, v100, v133
	v_fmac_f32_e32 v210, v101, v133
	v_fmac_f32_e32 v211, v102, v133
	v_fmac_f32_e32 v212, v103, v133
	v_fmac_f32_e32 v213, v104, v133
	v_fmac_f32_e32 v214, v105, v133
	v_fmac_f32_e32 v215, v106, v133
	v_fmac_f32_e32 v216, v107, v133
	v_fmac_f32_e32 v217, v108, v133
	v_fmac_f32_e32 v218, v109, v133
	v_fmac_f32_e32 v219, v110, v133
	v_fmac_f32_e32 v220, v111, v133
	s_mov_b64 s[38:39], s[68:69]
	s_and_b64 vcc, exec, s[18:19]
	s_cbranch_vccnz .Lg4s2_done
	s_add_i32 s0, s4, 64
	s_cmp_lt_i32 s0, s33
	s_cselect_b32 s38, s76, s78
	s_cselect_b32 s39, s77, s79
	s_cbranch_scc1 .Lg4s2_done
	s_sub_u32 s38, s38, 0x2000000
	s_subb_u32 s39, s39, 0
.Lg4s2_done:
	s_add_u32 s0, s38, 0x40000
	s_addc_u32 s1, s39, 0
	global_load_dword v0, v221, s[0:1]
	global_load_dword v16, v221, s[0:1] offset:128
	s_add_u32 s0, s38, 0x41000
	s_addc_u32 s1, s39, 0
	global_load_dword v1, v221, s[0:1]
	global_load_dword v17, v221, s[0:1] offset:128
	s_add_u32 s0, s38, 0x42000
	s_addc_u32 s1, s39, 0
	global_load_dword v2, v221, s[0:1]
	global_load_dword v18, v221, s[0:1] offset:128
	s_add_u32 s0, s38, 0x43000
	s_addc_u32 s1, s39, 0
	global_load_dword v3, v221, s[0:1]
	global_load_dword v19, v221, s[0:1] offset:128
	s_add_u32 s0, s38, 0x48000
	s_addc_u32 s1, s39, 0
	global_load_dword v4, v221, s[0:1]
	global_load_dword v20, v221, s[0:1] offset:128
	s_add_u32 s0, s38, 0x49000
	s_addc_u32 s1, s39, 0
	global_load_dword v5, v221, s[0:1]
	global_load_dword v21, v221, s[0:1] offset:128
	s_add_u32 s0, s38, 0x4a000
	s_addc_u32 s1, s39, 0
	global_load_dword v6, v221, s[0:1]
	global_load_dword v22, v221, s[0:1] offset:128
	s_add_u32 s0, s38, 0x4b000
	s_addc_u32 s1, s39, 0
	global_load_dword v7, v221, s[0:1]
	global_load_dword v23, v221, s[0:1] offset:128
	s_add_u32 s0, s38, 0x50000
	s_addc_u32 s1, s39, 0
	global_load_dword v8, v221, s[0:1]
	global_load_dword v24, v221, s[0:1] offset:128
	s_add_u32 s0, s38, 0x51000
	s_addc_u32 s1, s39, 0
	global_load_dword v9, v221, s[0:1]
	global_load_dword v25, v221, s[0:1] offset:128
	s_add_u32 s0, s38, 0x52000
	s_addc_u32 s1, s39, 0
	global_load_dword v10, v221, s[0:1]
	global_load_dword v26, v221, s[0:1] offset:128
	s_add_u32 s0, s38, 0x53000
	s_addc_u32 s1, s39, 0
	global_load_dword v11, v221, s[0:1]
	global_load_dword v27, v221, s[0:1] offset:128
	s_add_u32 s0, s38, 0x58000
	s_addc_u32 s1, s39, 0
	global_load_dword v12, v221, s[0:1]
	global_load_dword v28, v221, s[0:1] offset:128
	s_add_u32 s0, s38, 0x59000
	s_addc_u32 s1, s39, 0
	global_load_dword v13, v221, s[0:1]
	global_load_dword v29, v221, s[0:1] offset:128
	s_add_u32 s0, s38, 0x5a000
	s_addc_u32 s1, s39, 0
	global_load_dword v14, v221, s[0:1]
	global_load_dword v30, v221, s[0:1] offset:128
	s_add_u32 s0, s38, 0x5b000
	s_addc_u32 s1, s39, 0
	global_load_dword v15, v221, s[0:1]
	global_load_dword v31, v221, s[0:1] offset:128
	s_waitcnt vmcnt(32)
	v_fmac_f32_e32 v150, v80, v142
	v_fmac_f32_e32 v151, v81, v142
	v_fmac_f32_e32 v152, v82, v142
	v_fmac_f32_e32 v153, v83, v142
	v_fmac_f32_e32 v154, v84, v142
	v_fmac_f32_e32 v155, v85, v142
	v_fmac_f32_e32 v156, v86, v142
	v_fmac_f32_e32 v157, v87, v142
	v_fmac_f32_e32 v158, v88, v142
	v_fmac_f32_e32 v159, v89, v142
	v_fmac_f32_e32 v160, v90, v142
	v_fmac_f32_e32 v161, v91, v142
	v_fmac_f32_e32 v162, v92, v142
	v_fmac_f32_e32 v163, v93, v142
	v_fmac_f32_e32 v164, v94, v142
	v_fmac_f32_e32 v165, v95, v142
	v_fmac_f32_e32 v172, v64, v143
	v_fmac_f32_e32 v173, v65, v143
	v_fmac_f32_e32 v174, v66, v143
	v_fmac_f32_e32 v175, v67, v143
	v_fmac_f32_e32 v176, v68, v143
	v_fmac_f32_e32 v177, v69, v143
	v_fmac_f32_e32 v178, v70, v143
	v_fmac_f32_e32 v179, v71, v143
	v_fmac_f32_e32 v180, v72, v143
	v_fmac_f32_e32 v181, v73, v143
	v_fmac_f32_e32 v182, v74, v143
	v_fmac_f32_e32 v183, v75, v143
	v_fmac_f32_e32 v184, v76, v143
	v_fmac_f32_e32 v185, v77, v143
	v_fmac_f32_e32 v186, v78, v143
	v_fmac_f32_e32 v187, v79, v143
	s_waitcnt vmcnt(0)
	v_fmac_f32_e32 v0, v48, v144
	v_fmac_f32_e32 v1, v49, v144
	v_fmac_f32_e32 v2, v50, v144
	v_fmac_f32_e32 v3, v51, v144
	v_fmac_f32_e32 v4, v52, v144
	v_fmac_f32_e32 v5, v53, v144
	v_fmac_f32_e32 v6, v54, v144
	v_fmac_f32_e32 v7, v55, v144
	v_fmac_f32_e32 v8, v56, v144
	v_fmac_f32_e32 v9, v57, v144
	v_fmac_f32_e32 v10, v58, v144
	v_fmac_f32_e32 v11, v59, v144
	v_fmac_f32_e32 v12, v60, v144
	v_fmac_f32_e32 v13, v61, v144
	v_fmac_f32_e32 v14, v62, v144
	v_fmac_f32_e32 v15, v63, v144
	v_fmac_f32_e32 v16, v32, v145
	v_fmac_f32_e32 v17, v33, v145
	v_fmac_f32_e32 v18, v34, v145
	v_fmac_f32_e32 v19, v35, v145
	v_fmac_f32_e32 v20, v36, v145
	v_fmac_f32_e32 v21, v37, v145
	v_fmac_f32_e32 v22, v38, v145
	v_fmac_f32_e32 v23, v39, v145
	v_fmac_f32_e32 v24, v40, v145
	v_fmac_f32_e32 v25, v41, v145
	v_fmac_f32_e32 v26, v42, v145
	v_fmac_f32_e32 v27, v43, v145
	v_fmac_f32_e32 v28, v44, v145
	v_fmac_f32_e32 v29, v45, v145
	v_fmac_f32_e32 v30, v46, v145
	v_fmac_f32_e32 v31, v47, v145
	s_mov_b32 s0, s68
	s_mov_b32 s1, s69
	global_store_dword v221, v189, s[0:1]
	global_store_dword v221, v205, s[0:1] offset:128
	s_add_u32 s0, s68, 0x1000
	s_addc_u32 s1, s69, 0
	global_store_dword v221, v190, s[0:1]
	global_store_dword v221, v206, s[0:1] offset:128
	s_add_u32 s0, s68, 0x2000
	s_addc_u32 s1, s69, 0
	global_store_dword v221, v191, s[0:1]
	global_store_dword v221, v207, s[0:1] offset:128
	s_add_u32 s0, s68, 0x3000
	s_addc_u32 s1, s69, 0
	global_store_dword v221, v192, s[0:1]
	global_store_dword v221, v208, s[0:1] offset:128
	s_add_u32 s0, s68, 0x8000
	s_addc_u32 s1, s69, 0
	global_store_dword v221, v193, s[0:1]
	global_store_dword v221, v209, s[0:1] offset:128
	s_add_u32 s0, s68, 0x9000
	s_addc_u32 s1, s69, 0
	global_store_dword v221, v194, s[0:1]
	global_store_dword v221, v210, s[0:1] offset:128
	s_add_u32 s0, s68, 0xa000
	s_addc_u32 s1, s69, 0
	global_store_dword v221, v195, s[0:1]
	global_store_dword v221, v211, s[0:1] offset:128
	s_add_u32 s0, s68, 0xb000
	s_addc_u32 s1, s69, 0
	global_store_dword v221, v196, s[0:1]
	global_store_dword v221, v212, s[0:1] offset:128
	s_add_u32 s0, s68, 0x10000
	s_addc_u32 s1, s69, 0
	global_store_dword v221, v197, s[0:1]
	global_store_dword v221, v213, s[0:1] offset:128
	s_add_u32 s0, s68, 0x11000
	s_addc_u32 s1, s69, 0
	global_store_dword v221, v198, s[0:1]
	global_store_dword v221, v214, s[0:1] offset:128
	s_add_u32 s0, s68, 0x12000
	s_addc_u32 s1, s69, 0
	global_store_dword v221, v199, s[0:1]
	global_store_dword v221, v215, s[0:1] offset:128
	s_add_u32 s0, s68, 0x13000
	s_addc_u32 s1, s69, 0
	global_store_dword v221, v200, s[0:1]
	global_store_dword v221, v216, s[0:1] offset:128
	s_add_u32 s0, s68, 0x18000
	s_addc_u32 s1, s69, 0
	global_store_dword v221, v201, s[0:1]
	global_store_dword v221, v217, s[0:1] offset:128
	s_add_u32 s0, s68, 0x19000
	s_addc_u32 s1, s69, 0
	global_store_dword v221, v202, s[0:1]
	global_store_dword v221, v218, s[0:1] offset:128
	s_add_u32 s0, s68, 0x1a000
	s_addc_u32 s1, s69, 0
	global_store_dword v221, v203, s[0:1]
	global_store_dword v221, v219, s[0:1] offset:128
	s_add_u32 s0, s68, 0x1b000
	s_addc_u32 s1, s69, 0
	global_store_dword v221, v204, s[0:1]
	global_store_dword v221, v220, s[0:1] offset:128
	s_add_u32 s0, s68, 0x20000
	s_addc_u32 s1, s69, 0
	global_store_dword v221, v150, s[0:1]
	global_store_dword v221, v172, s[0:1] offset:128
	s_add_u32 s0, s68, 0x21000
	s_addc_u32 s1, s69, 0
	global_store_dword v221, v151, s[0:1]
	global_store_dword v221, v173, s[0:1] offset:128
	s_add_u32 s0, s68, 0x22000
	s_addc_u32 s1, s69, 0
	global_store_dword v221, v152, s[0:1]
	global_store_dword v221, v174, s[0:1] offset:128
	s_add_u32 s0, s68, 0x23000
	s_addc_u32 s1, s69, 0
	global_store_dword v221, v153, s[0:1]
	global_store_dword v221, v175, s[0:1] offset:128
	s_add_u32 s0, s68, 0x28000
	s_addc_u32 s1, s69, 0
	global_store_dword v221, v154, s[0:1]
	global_store_dword v221, v176, s[0:1] offset:128
	s_add_u32 s0, s68, 0x29000
	s_addc_u32 s1, s69, 0
	global_store_dword v221, v155, s[0:1]
	global_store_dword v221, v177, s[0:1] offset:128
	s_add_u32 s0, s68, 0x2a000
	s_addc_u32 s1, s69, 0
	global_store_dword v221, v156, s[0:1]
	global_store_dword v221, v178, s[0:1] offset:128
	s_add_u32 s0, s68, 0x2b000
	s_addc_u32 s1, s69, 0
	global_store_dword v221, v157, s[0:1]
	global_store_dword v221, v179, s[0:1] offset:128
	s_add_u32 s0, s68, 0x30000
	s_addc_u32 s1, s69, 0
	global_store_dword v221, v158, s[0:1]
	global_store_dword v221, v180, s[0:1] offset:128
	s_add_u32 s0, s68, 0x31000
	s_addc_u32 s1, s69, 0
	global_store_dword v221, v159, s[0:1]
	global_store_dword v221, v181, s[0:1] offset:128
	s_add_u32 s0, s68, 0x32000
	s_addc_u32 s1, s69, 0
	global_store_dword v221, v160, s[0:1]
	global_store_dword v221, v182, s[0:1] offset:128
	s_add_u32 s0, s68, 0x33000
	s_addc_u32 s1, s69, 0
	global_store_dword v221, v161, s[0:1]
	global_store_dword v221, v183, s[0:1] offset:128
	s_add_u32 s0, s68, 0x38000
	s_addc_u32 s1, s69, 0
	global_store_dword v221, v162, s[0:1]
	global_store_dword v221, v184, s[0:1] offset:128
	s_add_u32 s0, s68, 0x39000
	s_addc_u32 s1, s69, 0
	global_store_dword v221, v163, s[0:1]
	global_store_dword v221, v185, s[0:1] offset:128
	s_add_u32 s0, s68, 0x3a000
	s_addc_u32 s1, s69, 0
	global_store_dword v221, v164, s[0:1]
	global_store_dword v221, v186, s[0:1] offset:128
	s_add_u32 s0, s68, 0x3b000
	s_addc_u32 s1, s69, 0
	global_store_dword v221, v165, s[0:1]
	global_store_dword v221, v187, s[0:1] offset:128
	s_add_u32 s0, s68, 0x40000
	s_addc_u32 s1, s69, 0
	global_store_dword v221, v0, s[0:1]
	global_store_dword v221, v16, s[0:1] offset:128
	s_add_u32 s0, s68, 0x41000
	s_addc_u32 s1, s69, 0
	global_store_dword v221, v1, s[0:1]
	global_store_dword v221, v17, s[0:1] offset:128
	s_add_u32 s0, s68, 0x42000
	s_addc_u32 s1, s69, 0
	global_store_dword v221, v2, s[0:1]
	global_store_dword v221, v18, s[0:1] offset:128
	s_add_u32 s0, s68, 0x43000
	s_addc_u32 s1, s69, 0
	global_store_dword v221, v3, s[0:1]
	global_store_dword v221, v19, s[0:1] offset:128
	s_add_u32 s0, s68, 0x48000
	s_addc_u32 s1, s69, 0
	global_store_dword v221, v4, s[0:1]
	global_store_dword v221, v20, s[0:1] offset:128
	s_add_u32 s0, s68, 0x49000
	s_addc_u32 s1, s69, 0
	global_store_dword v221, v5, s[0:1]
	global_store_dword v221, v21, s[0:1] offset:128
	s_add_u32 s0, s68, 0x4a000
	s_addc_u32 s1, s69, 0
	global_store_dword v221, v6, s[0:1]
	global_store_dword v221, v22, s[0:1] offset:128
	s_add_u32 s0, s68, 0x4b000
	s_addc_u32 s1, s69, 0
	global_store_dword v221, v7, s[0:1]
	global_store_dword v221, v23, s[0:1] offset:128
	s_add_u32 s0, s68, 0x50000
	s_addc_u32 s1, s69, 0
	global_store_dword v221, v8, s[0:1]
	global_store_dword v221, v24, s[0:1] offset:128
	s_add_u32 s0, s68, 0x51000
	s_addc_u32 s1, s69, 0
	global_store_dword v221, v9, s[0:1]
	global_store_dword v221, v25, s[0:1] offset:128
	s_add_u32 s0, s68, 0x52000
	s_addc_u32 s1, s69, 0
	global_store_dword v221, v10, s[0:1]
	global_store_dword v221, v26, s[0:1] offset:128
	s_add_u32 s0, s68, 0x53000
	s_addc_u32 s1, s69, 0
	global_store_dword v221, v11, s[0:1]
	global_store_dword v221, v27, s[0:1] offset:128
	s_add_u32 s0, s68, 0x58000
	s_addc_u32 s1, s69, 0
	global_store_dword v221, v12, s[0:1]
	global_store_dword v221, v28, s[0:1] offset:128
	s_add_u32 s0, s68, 0x59000
	s_addc_u32 s1, s69, 0
	global_store_dword v221, v13, s[0:1]
	global_store_dword v221, v29, s[0:1] offset:128
	s_add_u32 s0, s68, 0x5a000
	s_addc_u32 s1, s69, 0
	global_store_dword v221, v14, s[0:1]
	global_store_dword v221, v30, s[0:1] offset:128
	s_add_u32 s0, s68, 0x5b000
	s_addc_u32 s1, s69, 0
	global_store_dword v221, v15, s[0:1]
	global_store_dword v221, v31, s[0:1] offset:128
	s_branch .LBB0_267
